# nt hint also on the final output stores of P12 (nothing reads them afterwards)
# baseline (speedup 1.0000x reference)
;     __device__ __forceinline__ void operator()(const f32x4 (&acc)[2][2][4][2], const pg8::Unit& u, int wr, int wc, int fr, int fq) const {
;         const int row0 = u.pm * 256 + wr * 64 + fr; const float* gp = gate + (size_t)(u.pm >> 5) * NMOD;
; #pragma unroll
;         for (int bj = 0; bj < 2; ++bj) {
;             const int col = u.pn * 256 + bj * 128 + wc * 32 + 8 * fq;
;             const f32x4 g0 = *(const f32x4*)(gp + col) * coef, g1 = *(const f32x4*)(gp + col + 4) * coef;
; #pragma unroll
;             for (int ai = 0; ai < 2; ++ai)
; #pragma unroll
;                 for (int m = 0; m < 4; ++m) {
;                     const size_t off = (size_t)(row0 + ai * 128 + m * 16) * DM + col;
;                     const f32x4 x0 = *(const f32x4*)(base + off), x1 = *(const f32x4*)(base + off + 4);
;                     *(f32x4*)(out + off) = x0 + g0 * acc[ai][bj][m][0]; *(f32x4*)(out + off + 4) = x1 + g1 * acc[ai][bj][m][1];
.LBB0_1396:
	v_and_b32_e32 v243, 8, v156
	v_sub_u32_e32 v240, v156, v243
	v_lshrrev_b32_e32 v243, 1, v243
	v_add_u32_e32 v241, v158, v243
	v_lshl_add_u32 v240, s47, 8, v240
	v_lshl_add_u32 v241, s48, 8, v241
	v_lshlrev_b32_e32 v240, 10, v240
	v_add_lshl_u32 v240, v240, v241, 2
	v_lshlrev_b32_e32 v241, 2, v241
	v_add_u32_e32 v242, 0x8000, v240
	s_ashr_i32 s98, s47, 5
	s_mul_i32 s98, s98, 0x9000
	s_add_u32 s98, s38, s98
	s_addc_u32 s99, s39, 0
	global_load_dwordx4 v[144:147], v241, s[98:99]
	s_add_u32 s100, s90, 0x0
	s_addc_u32 s101, s91, 0
	global_load_dwordx4 v[172:175], v240, s[100:101]
	global_load_dwordx4 v[176:179], v242, s[100:101]
	s_add_u32 s100, s90, 0x10000
	s_addc_u32 s101, s91, 0
	global_load_dwordx4 v[180:183], v240, s[100:101]
	global_load_dwordx4 v[184:187], v242, s[100:101]
	s_add_u32 s100, s90, 0x20000
	s_addc_u32 s101, s91, 0
	global_load_dwordx4 v[188:191], v240, s[100:101]
	global_load_dwordx4 v[192:195], v242, s[100:101]
	s_add_u32 s100, s90, 0x30000
	s_addc_u32 s101, s91, 0
	global_load_dwordx4 v[196:199], v240, s[100:101]
	global_load_dwordx4 v[200:203], v242, s[100:101]
	s_add_u32 s100, s90, 0x80000
	s_addc_u32 s101, s91, 0
	global_load_dwordx4 v[208:211], v240, s[100:101]
	global_load_dwordx4 v[212:215], v242, s[100:101]
	s_add_u32 s100, s90, 0x90000
	s_addc_u32 s101, s91, 0
	global_load_dwordx4 v[216:219], v240, s[100:101]
	global_load_dwordx4 v[220:223], v242, s[100:101]
	s_add_u32 s100, s90, 0xa0000
	s_addc_u32 s101, s91, 0
	global_load_dwordx4 v[224:227], v240, s[100:101]
	global_load_dwordx4 v[228:231], v242, s[100:101]
	s_add_u32 s100, s90, 0xb0000
	s_addc_u32 s101, s91, 0
	global_load_dwordx4 v[232:235], v240, s[100:101]
	global_load_dwordx4 v[236:239], v242, s[100:101]
	v_mov_b32_dpp v148, v120 row_ror:8 row_mask:0xf bank_mask:0xf
	v_mov_b32_dpp v149, v121 row_ror:8 row_mask:0xf bank_mask:0xf
	v_mov_b32_dpp v150, v122 row_ror:8 row_mask:0xf bank_mask:0xf
	v_mov_b32_dpp v151, v123 row_ror:8 row_mask:0xf bank_mask:0xf
	v_mov_b32_dpp v120, v124 row_ror:8 row_mask:0xf bank_mask:0x3
	v_mov_b32_dpp v121, v125 row_ror:8 row_mask:0xf bank_mask:0x3
	v_mov_b32_dpp v122, v126 row_ror:8 row_mask:0xf bank_mask:0x3
	v_mov_b32_dpp v123, v127 row_ror:8 row_mask:0xf bank_mask:0x3
	v_mov_b32_dpp v124, v148 quad_perm:[0,1,2,3] row_mask:0xf bank_mask:0xc
	v_mov_b32_dpp v125, v149 quad_perm:[0,1,2,3] row_mask:0xf bank_mask:0xc
	v_mov_b32_dpp v126, v150 quad_perm:[0,1,2,3] row_mask:0xf bank_mask:0xc
	v_mov_b32_dpp v127, v151 quad_perm:[0,1,2,3] row_mask:0xf bank_mask:0xc
	s_waitcnt vmcnt(16)
	v_pk_mul_f32 v[144:145], v[144:145], 0.5 op_sel_hi:[1,0]
	v_pk_mul_f32 v[146:147], v[146:147], 0.5 op_sel_hi:[1,0]
	s_waitcnt vmcnt(14)
	v_pk_fma_f32 v[124:125], v[124:125], v[144:145], v[172:173]
	v_pk_fma_f32 v[126:127], v[126:127], v[146:147], v[174:175]
	v_pk_fma_f32 v[120:121], v[120:121], v[144:145], v[176:177]
	v_pk_fma_f32 v[122:123], v[122:123], v[146:147], v[178:179]
	s_add_u32 s98, s90, 0x0
	s_addc_u32 s99, s91, 0
	global_store_dwordx4 v240, v[124:127], s[98:99] nt
	global_store_dwordx4 v242, v[120:123], s[98:99] nt
	s_add_u32 s100, s90, 0x0
	s_addc_u32 s101, s91, 0
	global_load_dwordx4 v[172:175], v240, s[100:101] offset:512
	global_load_dwordx4 v[176:179], v242, s[100:101] offset:512
	s_ashr_i32 s98, s47, 5
	s_mul_i32 s98, s98, 0x9000
	s_add_u32 s98, s38, s98
	s_addc_u32 s99, s39, 0
	global_load_dwordx4 v[120:123], v241, s[98:99] offset:512
	v_mov_b32_dpp v148, v112 row_ror:8 row_mask:0xf bank_mask:0xf
	v_mov_b32_dpp v149, v113 row_ror:8 row_mask:0xf bank_mask:0xf
	v_mov_b32_dpp v150, v114 row_ror:8 row_mask:0xf bank_mask:0xf
	v_mov_b32_dpp v151, v115 row_ror:8 row_mask:0xf bank_mask:0xf
	v_mov_b32_dpp v112, v116 row_ror:8 row_mask:0xf bank_mask:0x3
	v_mov_b32_dpp v113, v117 row_ror:8 row_mask:0xf bank_mask:0x3
	v_mov_b32_dpp v114, v118 row_ror:8 row_mask:0xf bank_mask:0x3
	v_mov_b32_dpp v115, v119 row_ror:8 row_mask:0xf bank_mask:0x3
	v_mov_b32_dpp v116, v148 quad_perm:[0,1,2,3] row_mask:0xf bank_mask:0xc
	v_mov_b32_dpp v117, v149 quad_perm:[0,1,2,3] row_mask:0xf bank_mask:0xc
	v_mov_b32_dpp v118, v150 quad_perm:[0,1,2,3] row_mask:0xf bank_mask:0xc
	v_mov_b32_dpp v119, v151 quad_perm:[0,1,2,3] row_mask:0xf bank_mask:0xc
	s_waitcnt vmcnt(17)
	v_pk_fma_f32 v[116:117], v[116:117], v[144:145], v[180:181]
	v_pk_fma_f32 v[118:119], v[118:119], v[146:147], v[182:183]
	v_pk_fma_f32 v[112:113], v[112:113], v[144:145], v[184:185]
	v_pk_fma_f32 v[114:115], v[114:115], v[146:147], v[186:187]
	s_add_u32 s98, s90, 0x10000
	s_addc_u32 s99, s91, 0
	global_store_dwordx4 v240, v[116:119], s[98:99] nt
	global_store_dwordx4 v242, v[112:115], s[98:99] nt
	s_add_u32 s100, s90, 0x10000
	s_addc_u32 s101, s91, 0
	global_load_dwordx4 v[180:183], v240, s[100:101] offset:512
	global_load_dwordx4 v[184:187], v242, s[100:101] offset:512
	v_mov_b32_dpp v148, v104 row_ror:8 row_mask:0xf bank_mask:0xf
	v_mov_b32_dpp v149, v105 row_ror:8 row_mask:0xf bank_mask:0xf
	v_mov_b32_dpp v150, v106 row_ror:8 row_mask:0xf bank_mask:0xf
	v_mov_b32_dpp v151, v107 row_ror:8 row_mask:0xf bank_mask:0xf
	v_mov_b32_dpp v104, v108 row_ror:8 row_mask:0xf bank_mask:0x3
	v_mov_b32_dpp v105, v109 row_ror:8 row_mask:0xf bank_mask:0x3
	v_mov_b32_dpp v106, v110 row_ror:8 row_mask:0xf bank_mask:0x3
	v_mov_b32_dpp v107, v111 row_ror:8 row_mask:0xf bank_mask:0x3
	v_mov_b32_dpp v108, v148 quad_perm:[0,1,2,3] row_mask:0xf bank_mask:0xc
	v_mov_b32_dpp v109, v149 quad_perm:[0,1,2,3] row_mask:0xf bank_mask:0xc
	v_mov_b32_dpp v110, v150 quad_perm:[0,1,2,3] row_mask:0xf bank_mask:0xc
	v_mov_b32_dpp v111, v151 quad_perm:[0,1,2,3] row_mask:0xf bank_mask:0xc
	s_waitcnt vmcnt(19)
;     __device__ __forceinline__ void operator()(const f32x4 (&acc)[2][2][4][2], const pg8::Unit& u, int wr, int wc, int fr, int fq) const {
;     ...
;             for (int ai = 0; ai < 2; ++ai)
; #pragma unroll
;                 for (int m = 0; m < 4; ++m) {
;                     const size_t off = (size_t)(row0 + ai * 128 + m * 16) * DM + col;
;                     const f32x4 x0 = *(const f32x4*)(base + off), x1 = *(const f32x4*)(base + off + 4);
;                     *(f32x4*)(out + off) = x0 + g0 * acc[ai][bj][m][0]; *(f32x4*)(out + off + 4) = x1 + g1 * acc[ai][bj][m][1];
;                     if (m & 1) asm volatile("" ::: "memory");
	v_pk_fma_f32 v[108:109], v[108:109], v[144:145], v[188:189]
	v_pk_fma_f32 v[110:111], v[110:111], v[146:147], v[190:191]
	v_pk_fma_f32 v[104:105], v[104:105], v[144:145], v[192:193]
	v_pk_fma_f32 v[106:107], v[106:107], v[146:147], v[194:195]
	s_add_u32 s98, s90, 0x20000
	s_addc_u32 s99, s91, 0
	global_store_dwordx4 v240, v[108:111], s[98:99] nt
	global_store_dwordx4 v242, v[104:107], s[98:99] nt
	s_add_u32 s100, s90, 0x20000
	s_addc_u32 s101, s91, 0
	global_load_dwordx4 v[188:191], v240, s[100:101] offset:512
	global_load_dwordx4 v[192:195], v242, s[100:101] offset:512
	v_mov_b32_dpp v148, v96 row_ror:8 row_mask:0xf bank_mask:0xf
	v_mov_b32_dpp v149, v97 row_ror:8 row_mask:0xf bank_mask:0xf
	v_mov_b32_dpp v150, v98 row_ror:8 row_mask:0xf bank_mask:0xf
	v_mov_b32_dpp v151, v99 row_ror:8 row_mask:0xf bank_mask:0xf
	v_mov_b32_dpp v96, v100 row_ror:8 row_mask:0xf bank_mask:0x3
	v_mov_b32_dpp v97, v101 row_ror:8 row_mask:0xf bank_mask:0x3
	v_mov_b32_dpp v98, v102 row_ror:8 row_mask:0xf bank_mask:0x3
	v_mov_b32_dpp v99, v103 row_ror:8 row_mask:0xf bank_mask:0x3
	v_mov_b32_dpp v100, v148 quad_perm:[0,1,2,3] row_mask:0xf bank_mask:0xc
	v_mov_b32_dpp v101, v149 quad_perm:[0,1,2,3] row_mask:0xf bank_mask:0xc
	v_mov_b32_dpp v102, v150 quad_perm:[0,1,2,3] row_mask:0xf bank_mask:0xc
	v_mov_b32_dpp v103, v151 quad_perm:[0,1,2,3] row_mask:0xf bank_mask:0xc
	s_waitcnt vmcnt(21)
	v_pk_fma_f32 v[100:101], v[100:101], v[144:145], v[196:197]
	v_pk_fma_f32 v[102:103], v[102:103], v[146:147], v[198:199]
	v_pk_fma_f32 v[96:97], v[96:97], v[144:145], v[200:201]
	v_pk_fma_f32 v[98:99], v[98:99], v[146:147], v[202:203]
	s_add_u32 s98, s90, 0x30000
	s_addc_u32 s99, s91, 0
	global_store_dwordx4 v240, v[100:103], s[98:99] nt
	global_store_dwordx4 v242, v[96:99], s[98:99] nt
	s_add_u32 s100, s90, 0x30000
	s_addc_u32 s101, s91, 0
	global_load_dwordx4 v[196:199], v240, s[100:101] offset:512
	global_load_dwordx4 v[200:203], v242, s[100:101] offset:512
	v_mov_b32_dpp v148, v88 row_ror:8 row_mask:0xf bank_mask:0xf
	v_mov_b32_dpp v149, v89 row_ror:8 row_mask:0xf bank_mask:0xf
	v_mov_b32_dpp v150, v90 row_ror:8 row_mask:0xf bank_mask:0xf
	v_mov_b32_dpp v151, v91 row_ror:8 row_mask:0xf bank_mask:0xf
	v_mov_b32_dpp v88, v92 row_ror:8 row_mask:0xf bank_mask:0x3
	v_mov_b32_dpp v89, v93 row_ror:8 row_mask:0xf bank_mask:0x3
	v_mov_b32_dpp v90, v94 row_ror:8 row_mask:0xf bank_mask:0x3
	v_mov_b32_dpp v91, v95 row_ror:8 row_mask:0xf bank_mask:0x3
	v_mov_b32_dpp v92, v148 quad_perm:[0,1,2,3] row_mask:0xf bank_mask:0xc
	v_mov_b32_dpp v93, v149 quad_perm:[0,1,2,3] row_mask:0xf bank_mask:0xc
	v_mov_b32_dpp v94, v150 quad_perm:[0,1,2,3] row_mask:0xf bank_mask:0xc
	v_mov_b32_dpp v95, v151 quad_perm:[0,1,2,3] row_mask:0xf bank_mask:0xc
	s_waitcnt vmcnt(23)
	v_pk_fma_f32 v[92:93], v[92:93], v[144:145], v[208:209]
	v_pk_fma_f32 v[94:95], v[94:95], v[146:147], v[210:211]
	v_pk_fma_f32 v[88:89], v[88:89], v[144:145], v[212:213]
	v_pk_fma_f32 v[90:91], v[90:91], v[146:147], v[214:215]
	s_add_u32 s98, s90, 0x80000
	s_addc_u32 s99, s91, 0
	global_store_dwordx4 v240, v[92:95], s[98:99] nt
	global_store_dwordx4 v242, v[88:91], s[98:99] nt
	s_add_u32 s100, s90, 0x80000
	s_addc_u32 s101, s91, 0
	global_load_dwordx4 v[208:211], v240, s[100:101] offset:512
	global_load_dwordx4 v[212:215], v242, s[100:101] offset:512
	v_mov_b32_dpp v148, v80 row_ror:8 row_mask:0xf bank_mask:0xf
	v_mov_b32_dpp v149, v81 row_ror:8 row_mask:0xf bank_mask:0xf
	v_mov_b32_dpp v150, v82 row_ror:8 row_mask:0xf bank_mask:0xf
	v_mov_b32_dpp v151, v83 row_ror:8 row_mask:0xf bank_mask:0xf
	v_mov_b32_dpp v80, v84 row_ror:8 row_mask:0xf bank_mask:0x3
	v_mov_b32_dpp v81, v85 row_ror:8 row_mask:0xf bank_mask:0x3
	v_mov_b32_dpp v82, v86 row_ror:8 row_mask:0xf bank_mask:0x3
	v_mov_b32_dpp v83, v87 row_ror:8 row_mask:0xf bank_mask:0x3
	v_mov_b32_dpp v84, v148 quad_perm:[0,1,2,3] row_mask:0xf bank_mask:0xc
	v_mov_b32_dpp v85, v149 quad_perm:[0,1,2,3] row_mask:0xf bank_mask:0xc
	v_mov_b32_dpp v86, v150 quad_perm:[0,1,2,3] row_mask:0xf bank_mask:0xc
	v_mov_b32_dpp v87, v151 quad_perm:[0,1,2,3] row_mask:0xf bank_mask:0xc
	s_waitcnt vmcnt(25)
	v_pk_fma_f32 v[84:85], v[84:85], v[144:145], v[216:217]
	v_pk_fma_f32 v[86:87], v[86:87], v[146:147], v[218:219]
	v_pk_fma_f32 v[80:81], v[80:81], v[144:145], v[220:221]
	v_pk_fma_f32 v[82:83], v[82:83], v[146:147], v[222:223]
	s_add_u32 s98, s90, 0x90000
	s_addc_u32 s99, s91, 0
	global_store_dwordx4 v240, v[84:87], s[98:99] nt
	global_store_dwordx4 v242, v[80:83], s[98:99] nt
	s_add_u32 s100, s90, 0x90000
	s_addc_u32 s101, s91, 0
	global_load_dwordx4 v[216:219], v240, s[100:101] offset:512
	global_load_dwordx4 v[220:223], v242, s[100:101] offset:512
	v_mov_b32_dpp v148, v72 row_ror:8 row_mask:0xf bank_mask:0xf
	v_mov_b32_dpp v149, v73 row_ror:8 row_mask:0xf bank_mask:0xf
	v_mov_b32_dpp v150, v74 row_ror:8 row_mask:0xf bank_mask:0xf
	v_mov_b32_dpp v151, v75 row_ror:8 row_mask:0xf bank_mask:0xf
	v_mov_b32_dpp v72, v76 row_ror:8 row_mask:0xf bank_mask:0x3
	v_mov_b32_dpp v73, v77 row_ror:8 row_mask:0xf bank_mask:0x3
	v_mov_b32_dpp v74, v78 row_ror:8 row_mask:0xf bank_mask:0x3
	v_mov_b32_dpp v75, v79 row_ror:8 row_mask:0xf bank_mask:0x3
	v_mov_b32_dpp v76, v148 quad_perm:[0,1,2,3] row_mask:0xf bank_mask:0xc
	v_mov_b32_dpp v77, v149 quad_perm:[0,1,2,3] row_mask:0xf bank_mask:0xc
	v_mov_b32_dpp v78, v150 quad_perm:[0,1,2,3] row_mask:0xf bank_mask:0xc
	v_mov_b32_dpp v79, v151 quad_perm:[0,1,2,3] row_mask:0xf bank_mask:0xc
	s_waitcnt vmcnt(27)
;     __device__ __forceinline__ void operator()(const f32x4 (&acc)[2][2][4][2], const pg8::Unit& u, int wr, int wc, int fr, int fq) const {
;     ...
;             for (int ai = 0; ai < 2; ++ai)
; #pragma unroll
;                 for (int m = 0; m < 4; ++m) {
;                     const size_t off = (size_t)(row0 + ai * 128 + m * 16) * DM + col;
;                     const f32x4 x0 = *(const f32x4*)(base + off), x1 = *(const f32x4*)(base + off + 4);
;                     *(f32x4*)(out + off) = x0 + g0 * acc[ai][bj][m][0]; *(f32x4*)(out + off + 4) = x1 + g1 * acc[ai][bj][m][1];
;                     if (m & 1) asm volatile("" ::: "memory");
	v_pk_fma_f32 v[76:77], v[76:77], v[144:145], v[224:225]
	v_pk_fma_f32 v[78:79], v[78:79], v[146:147], v[226:227]
	v_pk_fma_f32 v[72:73], v[72:73], v[144:145], v[228:229]
	v_pk_fma_f32 v[74:75], v[74:75], v[146:147], v[230:231]
	s_add_u32 s98, s90, 0xa0000
	s_addc_u32 s99, s91, 0
	global_store_dwordx4 v240, v[76:79], s[98:99] nt
	global_store_dwordx4 v242, v[72:75], s[98:99] nt
	s_add_u32 s100, s90, 0xa0000
	s_addc_u32 s101, s91, 0
	global_load_dwordx4 v[224:227], v240, s[100:101] offset:512
	global_load_dwordx4 v[228:231], v242, s[100:101] offset:512
	v_mov_b32_dpp v148, v64 row_ror:8 row_mask:0xf bank_mask:0xf
	v_mov_b32_dpp v149, v65 row_ror:8 row_mask:0xf bank_mask:0xf
	v_mov_b32_dpp v150, v66 row_ror:8 row_mask:0xf bank_mask:0xf
	v_mov_b32_dpp v151, v67 row_ror:8 row_mask:0xf bank_mask:0xf
	v_mov_b32_dpp v64, v68 row_ror:8 row_mask:0xf bank_mask:0x3
	v_mov_b32_dpp v65, v69 row_ror:8 row_mask:0xf bank_mask:0x3
	v_mov_b32_dpp v66, v70 row_ror:8 row_mask:0xf bank_mask:0x3
	v_mov_b32_dpp v67, v71 row_ror:8 row_mask:0xf bank_mask:0x3
	v_mov_b32_dpp v68, v148 quad_perm:[0,1,2,3] row_mask:0xf bank_mask:0xc
	v_mov_b32_dpp v69, v149 quad_perm:[0,1,2,3] row_mask:0xf bank_mask:0xc
	v_mov_b32_dpp v70, v150 quad_perm:[0,1,2,3] row_mask:0xf bank_mask:0xc
	v_mov_b32_dpp v71, v151 quad_perm:[0,1,2,3] row_mask:0xf bank_mask:0xc
	s_waitcnt vmcnt(29)
	v_pk_fma_f32 v[68:69], v[68:69], v[144:145], v[232:233]
	v_pk_fma_f32 v[70:71], v[70:71], v[146:147], v[234:235]
	v_pk_fma_f32 v[64:65], v[64:65], v[144:145], v[236:237]
	v_pk_fma_f32 v[66:67], v[66:67], v[146:147], v[238:239]
	s_add_u32 s98, s90, 0xb0000
	s_addc_u32 s99, s91, 0
	global_store_dwordx4 v240, v[68:71], s[98:99] nt
	global_store_dwordx4 v242, v[64:67], s[98:99] nt
	s_add_u32 s100, s90, 0xb0000
	s_addc_u32 s101, s91, 0
	global_load_dwordx4 v[232:235], v240, s[100:101] offset:512
	global_load_dwordx4 v[236:239], v242, s[100:101] offset:512
	v_mov_b32_dpp v148, v56 row_ror:8 row_mask:0xf bank_mask:0xf
	v_mov_b32_dpp v149, v57 row_ror:8 row_mask:0xf bank_mask:0xf
	v_mov_b32_dpp v150, v58 row_ror:8 row_mask:0xf bank_mask:0xf
	v_mov_b32_dpp v151, v59 row_ror:8 row_mask:0xf bank_mask:0xf
	v_mov_b32_dpp v56, v60 row_ror:8 row_mask:0xf bank_mask:0x3
	v_mov_b32_dpp v57, v61 row_ror:8 row_mask:0xf bank_mask:0x3
	v_mov_b32_dpp v58, v62 row_ror:8 row_mask:0xf bank_mask:0x3
	v_mov_b32_dpp v59, v63 row_ror:8 row_mask:0xf bank_mask:0x3
	v_mov_b32_dpp v60, v148 quad_perm:[0,1,2,3] row_mask:0xf bank_mask:0xc
	v_mov_b32_dpp v61, v149 quad_perm:[0,1,2,3] row_mask:0xf bank_mask:0xc
	v_mov_b32_dpp v62, v150 quad_perm:[0,1,2,3] row_mask:0xf bank_mask:0xc
	v_mov_b32_dpp v63, v151 quad_perm:[0,1,2,3] row_mask:0xf bank_mask:0xc
	s_waitcnt vmcnt(28)
	v_pk_mul_f32 v[120:121], v[120:121], 0.5 op_sel_hi:[1,0]
	v_pk_mul_f32 v[122:123], v[122:123], 0.5 op_sel_hi:[1,0]
	v_pk_fma_f32 v[60:61], v[60:61], v[120:121], v[172:173]
	v_pk_fma_f32 v[62:63], v[62:63], v[122:123], v[174:175]
	v_pk_fma_f32 v[56:57], v[56:57], v[120:121], v[176:177]
	v_pk_fma_f32 v[58:59], v[58:59], v[122:123], v[178:179]
	s_add_u32 s98, s90, 0x0
	s_addc_u32 s99, s91, 0
	global_store_dwordx4 v240, v[60:63], s[98:99] offset:512 nt
	global_store_dwordx4 v242, v[56:59], s[98:99] offset:512 nt
	v_mov_b32_dpp v148, v48 row_ror:8 row_mask:0xf bank_mask:0xf
	v_mov_b32_dpp v149, v49 row_ror:8 row_mask:0xf bank_mask:0xf
	v_mov_b32_dpp v150, v50 row_ror:8 row_mask:0xf bank_mask:0xf
	v_mov_b32_dpp v151, v51 row_ror:8 row_mask:0xf bank_mask:0xf
	v_mov_b32_dpp v48, v52 row_ror:8 row_mask:0xf bank_mask:0x3
	v_mov_b32_dpp v49, v53 row_ror:8 row_mask:0xf bank_mask:0x3
	v_mov_b32_dpp v50, v54 row_ror:8 row_mask:0xf bank_mask:0x3
	v_mov_b32_dpp v51, v55 row_ror:8 row_mask:0xf bank_mask:0x3
	v_mov_b32_dpp v52, v148 quad_perm:[0,1,2,3] row_mask:0xf bank_mask:0xc
	v_mov_b32_dpp v53, v149 quad_perm:[0,1,2,3] row_mask:0xf bank_mask:0xc
	v_mov_b32_dpp v54, v150 quad_perm:[0,1,2,3] row_mask:0xf bank_mask:0xc
	v_mov_b32_dpp v55, v151 quad_perm:[0,1,2,3] row_mask:0xf bank_mask:0xc
	s_waitcnt vmcnt(26)
	v_pk_fma_f32 v[52:53], v[52:53], v[120:121], v[180:181]
	v_pk_fma_f32 v[54:55], v[54:55], v[122:123], v[182:183]
	v_pk_fma_f32 v[48:49], v[48:49], v[120:121], v[184:185]
	v_pk_fma_f32 v[50:51], v[50:51], v[122:123], v[186:187]
	s_add_u32 s98, s90, 0x10000
	s_addc_u32 s99, s91, 0
	global_store_dwordx4 v240, v[52:55], s[98:99] offset:512 nt
	global_store_dwordx4 v242, v[48:51], s[98:99] offset:512 nt
	v_mov_b32_dpp v148, v40 row_ror:8 row_mask:0xf bank_mask:0xf
	v_mov_b32_dpp v149, v41 row_ror:8 row_mask:0xf bank_mask:0xf
	v_mov_b32_dpp v150, v42 row_ror:8 row_mask:0xf bank_mask:0xf
	v_mov_b32_dpp v151, v43 row_ror:8 row_mask:0xf bank_mask:0xf
	v_mov_b32_dpp v40, v44 row_ror:8 row_mask:0xf bank_mask:0x3
	v_mov_b32_dpp v41, v45 row_ror:8 row_mask:0xf bank_mask:0x3
	v_mov_b32_dpp v42, v46 row_ror:8 row_mask:0xf bank_mask:0x3
	v_mov_b32_dpp v43, v47 row_ror:8 row_mask:0xf bank_mask:0x3
	v_mov_b32_dpp v44, v148 quad_perm:[0,1,2,3] row_mask:0xf bank_mask:0xc
	v_mov_b32_dpp v45, v149 quad_perm:[0,1,2,3] row_mask:0xf bank_mask:0xc
	v_mov_b32_dpp v46, v150 quad_perm:[0,1,2,3] row_mask:0xf bank_mask:0xc
	v_mov_b32_dpp v47, v151 quad_perm:[0,1,2,3] row_mask:0xf bank_mask:0xc
	s_waitcnt vmcnt(24)
;     __device__ __forceinline__ void operator()(const f32x4 (&acc)[2][2][4][2], const pg8::Unit& u, int wr, int wc, int fr, int fq) const {
;     ...
;             for (int ai = 0; ai < 2; ++ai)
; #pragma unroll
;                 for (int m = 0; m < 4; ++m) {
;                     const size_t off = (size_t)(row0 + ai * 128 + m * 16) * DM + col;
;                     const f32x4 x0 = *(const f32x4*)(base + off), x1 = *(const f32x4*)(base + off + 4);
;                     *(f32x4*)(out + off) = x0 + g0 * acc[ai][bj][m][0]; *(f32x4*)(out + off + 4) = x1 + g1 * acc[ai][bj][m][1];
;                     if (m & 1) asm volatile("" ::: "memory");
;                 }
;         }
	v_pk_fma_f32 v[44:45], v[44:45], v[120:121], v[188:189]
	v_pk_fma_f32 v[46:47], v[46:47], v[122:123], v[190:191]
	v_pk_fma_f32 v[40:41], v[40:41], v[120:121], v[192:193]
	v_pk_fma_f32 v[42:43], v[42:43], v[122:123], v[194:195]
	s_add_u32 s98, s90, 0x20000
	s_addc_u32 s99, s91, 0
	global_store_dwordx4 v240, v[44:47], s[98:99] offset:512 nt
	global_store_dwordx4 v242, v[40:43], s[98:99] offset:512 nt
	v_mov_b32_dpp v148, v32 row_ror:8 row_mask:0xf bank_mask:0xf
	v_mov_b32_dpp v149, v33 row_ror:8 row_mask:0xf bank_mask:0xf
	v_mov_b32_dpp v150, v34 row_ror:8 row_mask:0xf bank_mask:0xf
	v_mov_b32_dpp v151, v35 row_ror:8 row_mask:0xf bank_mask:0xf
	v_mov_b32_dpp v32, v36 row_ror:8 row_mask:0xf bank_mask:0x3
	v_mov_b32_dpp v33, v37 row_ror:8 row_mask:0xf bank_mask:0x3
	v_mov_b32_dpp v34, v38 row_ror:8 row_mask:0xf bank_mask:0x3
	v_mov_b32_dpp v35, v39 row_ror:8 row_mask:0xf bank_mask:0x3
	v_mov_b32_dpp v36, v148 quad_perm:[0,1,2,3] row_mask:0xf bank_mask:0xc
	v_mov_b32_dpp v37, v149 quad_perm:[0,1,2,3] row_mask:0xf bank_mask:0xc
	v_mov_b32_dpp v38, v150 quad_perm:[0,1,2,3] row_mask:0xf bank_mask:0xc
	v_mov_b32_dpp v39, v151 quad_perm:[0,1,2,3] row_mask:0xf bank_mask:0xc
	s_waitcnt vmcnt(22)
	v_pk_fma_f32 v[36:37], v[36:37], v[120:121], v[196:197]
	v_pk_fma_f32 v[38:39], v[38:39], v[122:123], v[198:199]
	v_pk_fma_f32 v[32:33], v[32:33], v[120:121], v[200:201]
	v_pk_fma_f32 v[34:35], v[34:35], v[122:123], v[202:203]
	s_add_u32 s98, s90, 0x30000
	s_addc_u32 s99, s91, 0
	global_store_dwordx4 v240, v[36:39], s[98:99] offset:512 nt
	global_store_dwordx4 v242, v[32:35], s[98:99] offset:512 nt
	v_mov_b32_dpp v148, v24 row_ror:8 row_mask:0xf bank_mask:0xf
	v_mov_b32_dpp v149, v25 row_ror:8 row_mask:0xf bank_mask:0xf
	v_mov_b32_dpp v150, v26 row_ror:8 row_mask:0xf bank_mask:0xf
	v_mov_b32_dpp v151, v27 row_ror:8 row_mask:0xf bank_mask:0xf
	v_mov_b32_dpp v24, v28 row_ror:8 row_mask:0xf bank_mask:0x3
	v_mov_b32_dpp v25, v29 row_ror:8 row_mask:0xf bank_mask:0x3
	v_mov_b32_dpp v26, v30 row_ror:8 row_mask:0xf bank_mask:0x3
	v_mov_b32_dpp v27, v31 row_ror:8 row_mask:0xf bank_mask:0x3
	v_mov_b32_dpp v28, v148 quad_perm:[0,1,2,3] row_mask:0xf bank_mask:0xc
	v_mov_b32_dpp v29, v149 quad_perm:[0,1,2,3] row_mask:0xf bank_mask:0xc
	v_mov_b32_dpp v30, v150 quad_perm:[0,1,2,3] row_mask:0xf bank_mask:0xc
	v_mov_b32_dpp v31, v151 quad_perm:[0,1,2,3] row_mask:0xf bank_mask:0xc
	s_waitcnt vmcnt(20)
	v_pk_fma_f32 v[28:29], v[28:29], v[120:121], v[208:209]
	v_pk_fma_f32 v[30:31], v[30:31], v[122:123], v[210:211]
	v_pk_fma_f32 v[24:25], v[24:25], v[120:121], v[212:213]
	v_pk_fma_f32 v[26:27], v[26:27], v[122:123], v[214:215]
	s_add_u32 s98, s90, 0x80000
	s_addc_u32 s99, s91, 0
	global_store_dwordx4 v240, v[28:31], s[98:99] offset:512 nt
	global_store_dwordx4 v242, v[24:27], s[98:99] offset:512 nt
	v_mov_b32_dpp v148, v16 row_ror:8 row_mask:0xf bank_mask:0xf
	v_mov_b32_dpp v149, v17 row_ror:8 row_mask:0xf bank_mask:0xf
	v_mov_b32_dpp v150, v18 row_ror:8 row_mask:0xf bank_mask:0xf
	v_mov_b32_dpp v151, v19 row_ror:8 row_mask:0xf bank_mask:0xf
	v_mov_b32_dpp v16, v20 row_ror:8 row_mask:0xf bank_mask:0x3
	v_mov_b32_dpp v17, v21 row_ror:8 row_mask:0xf bank_mask:0x3
	v_mov_b32_dpp v18, v22 row_ror:8 row_mask:0xf bank_mask:0x3
	v_mov_b32_dpp v19, v23 row_ror:8 row_mask:0xf bank_mask:0x3
	v_mov_b32_dpp v20, v148 quad_perm:[0,1,2,3] row_mask:0xf bank_mask:0xc
	v_mov_b32_dpp v21, v149 quad_perm:[0,1,2,3] row_mask:0xf bank_mask:0xc
	v_mov_b32_dpp v22, v150 quad_perm:[0,1,2,3] row_mask:0xf bank_mask:0xc
	v_mov_b32_dpp v23, v151 quad_perm:[0,1,2,3] row_mask:0xf bank_mask:0xc
	s_waitcnt vmcnt(18)
	v_pk_fma_f32 v[20:21], v[20:21], v[120:121], v[216:217]
	v_pk_fma_f32 v[22:23], v[22:23], v[122:123], v[218:219]
	v_pk_fma_f32 v[16:17], v[16:17], v[120:121], v[220:221]
	v_pk_fma_f32 v[18:19], v[18:19], v[122:123], v[222:223]
	s_add_u32 s98, s90, 0x90000
	s_addc_u32 s99, s91, 0
	global_store_dwordx4 v240, v[20:23], s[98:99] offset:512 nt
	global_store_dwordx4 v242, v[16:19], s[98:99] offset:512 nt
	v_mov_b32_dpp v148, v8 row_ror:8 row_mask:0xf bank_mask:0xf
	v_mov_b32_dpp v149, v9 row_ror:8 row_mask:0xf bank_mask:0xf
	v_mov_b32_dpp v150, v10 row_ror:8 row_mask:0xf bank_mask:0xf
	v_mov_b32_dpp v151, v11 row_ror:8 row_mask:0xf bank_mask:0xf
	v_mov_b32_dpp v8, v12 row_ror:8 row_mask:0xf bank_mask:0x3
	v_mov_b32_dpp v9, v13 row_ror:8 row_mask:0xf bank_mask:0x3
	v_mov_b32_dpp v10, v14 row_ror:8 row_mask:0xf bank_mask:0x3
	v_mov_b32_dpp v11, v15 row_ror:8 row_mask:0xf bank_mask:0x3
	v_mov_b32_dpp v12, v148 quad_perm:[0,1,2,3] row_mask:0xf bank_mask:0xc
	v_mov_b32_dpp v13, v149 quad_perm:[0,1,2,3] row_mask:0xf bank_mask:0xc
	v_mov_b32_dpp v14, v150 quad_perm:[0,1,2,3] row_mask:0xf bank_mask:0xc
	v_mov_b32_dpp v15, v151 quad_perm:[0,1,2,3] row_mask:0xf bank_mask:0xc
	s_waitcnt vmcnt(16)
	v_pk_fma_f32 v[12:13], v[12:13], v[120:121], v[224:225]
	v_pk_fma_f32 v[14:15], v[14:15], v[122:123], v[226:227]
	v_pk_fma_f32 v[8:9], v[8:9], v[120:121], v[228:229]
	v_pk_fma_f32 v[10:11], v[10:11], v[122:123], v[230:231]
	s_add_u32 s98, s90, 0xa0000
	s_addc_u32 s99, s91, 0
	global_store_dwordx4 v240, v[12:15], s[98:99] offset:512 nt
	global_store_dwordx4 v242, v[8:11], s[98:99] offset:512 nt
	v_mov_b32_dpp v148, v0 row_ror:8 row_mask:0xf bank_mask:0xf
	v_mov_b32_dpp v149, v1 row_ror:8 row_mask:0xf bank_mask:0xf
	v_mov_b32_dpp v150, v2 row_ror:8 row_mask:0xf bank_mask:0xf
	v_mov_b32_dpp v151, v3 row_ror:8 row_mask:0xf bank_mask:0xf
	v_mov_b32_dpp v0, v4 row_ror:8 row_mask:0xf bank_mask:0x3
	v_mov_b32_dpp v1, v5 row_ror:8 row_mask:0xf bank_mask:0x3
	v_mov_b32_dpp v2, v6 row_ror:8 row_mask:0xf bank_mask:0x3
	v_mov_b32_dpp v3, v7 row_ror:8 row_mask:0xf bank_mask:0x3
	v_mov_b32_dpp v4, v148 quad_perm:[0,1,2,3] row_mask:0xf bank_mask:0xc
	v_mov_b32_dpp v5, v149 quad_perm:[0,1,2,3] row_mask:0xf bank_mask:0xc
	v_mov_b32_dpp v6, v150 quad_perm:[0,1,2,3] row_mask:0xf bank_mask:0xc
	v_mov_b32_dpp v7, v151 quad_perm:[0,1,2,3] row_mask:0xf bank_mask:0xc
	s_waitcnt vmcnt(14)
	v_pk_fma_f32 v[4:5], v[4:5], v[120:121], v[232:233]
	v_pk_fma_f32 v[6:7], v[6:7], v[122:123], v[234:235]
	v_pk_fma_f32 v[0:1], v[0:1], v[120:121], v[236:237]
	v_pk_fma_f32 v[2:3], v[2:3], v[122:123], v[238:239]
	s_add_u32 s98, s90, 0xb0000
	s_addc_u32 s99, s91, 0
	global_store_dwordx4 v240, v[4:7], s[98:99] offset:512 nt
	global_store_dwordx4 v242, v[0:3], s[98:99] offset:512 nt
	s_and_b64 vcc, exec, s[0:1]
	s_mov_b64 s[0:1], -1
	s_cbranch_vccnz .LBB0_1381
	s_andn2_b64 vcc, exec, s[6:7]
	s_cbranch_vccnz .LBB0_1380
	s_barrier
	s_branch .LBB0_1380
